# v047 + EpiRes: f32 X stores as full 128-B lines per row (row_ror:8 DPP exchange, 8 rows per store instead of 16 half-lines)
# speedup vs baseline: 1.0282x; 1.0008x over previous
; __device__ __forceinline__ unsigned cvt_pk_bf16(float lo, float hi) { unsigned r; asm volatile("v_cvt_pk_bf16_f32 %0, %1, %2" : "=v"(r) : "v"(lo), "v"(hi)); return r; }
; __device__ __forceinline__ void st16f_wt(void* p, f32x4 v) { asm volatile("global_store_dwordx4 %0, %1, off sc1\n\ts_nop 1" :: "v"(p), "v"(v) : "memory"); }
; __device__ __forceinline__ void st8_wt(void* p, u32x2w v) { asm volatile("global_store_dwordx2 %0, %1, off sc1\n\ts_nop 1" :: "v"(p), "v"(v) : "memory"); }
;     __device__ __forceinline__ void operator()(const f32x4 (&acc)[2][2][4][2], const Unit& u, int wr, int wc, int fr, int fq) const {
;     ...
;             for (int bj = 0; bj < 2; ++bj)
; #pragma unroll
;                 for (int n = 0; n < 2; ++n) { f32x4 x = xc[bj][n] + (acc[ai][bj][m][n] + bv[bj][n]) * alpha; st16f_wt(X + off + bj * HALF + n * 16, x);
;                     if (XB) { u32x2w w; w.x = cvt_pk_bf16(x[0], x[1]); w.y = cvt_pk_bf16(x[2], x[3]); st8_wt(XB + off + bj * HALF + n * 16, w); }
.LBB0_532:
	s_or_b64 exec, exec, s[2:3]
	v_pk_add_f32 v[244:245], v[128:129], v[144:145]
	v_pk_add_f32 v[246:247], v[126:127], v[142:143]
	v_lshlrev_b64 v[206:207], 10, v[214:215]
	v_pk_fma_f32 v[176:177], v[244:245], s[94:95], v[176:177]
	v_pk_fma_f32 v[174:175], v[246:247], s[14:15], v[174:175]
	v_lshl_add_u64 v[222:223], v[218:219], 2, v[222:223]
	v_lshl_add_u64 v[206:207], v[206:207], 0, v[218:219]
	s_and_b64 vcc, exec, s[42:43]
	v_lshl_add_u64 v[206:207], v[206:207], 1, s[88:89]
	s_cbranch_vccz .LBB0_534
.LBB0_534:
	v_pk_add_f32 v[244:245], v[124:125], v[136:137]
	v_pk_add_f32 v[246:247], v[122:123], v[134:135]
	v_pk_fma_f32 v[188:189], v[244:245], s[94:95], v[188:189]
	v_pk_fma_f32 v[186:187], v[246:247], s[14:15], v[186:187]
	v_bfe_i32 v245, v233, 3, 1
	v_and_b32_e32 v244, 0xffff8040, v245
	v_lshl_add_u64 v[222:223], v[222:223], 0, v[244:245]
	s_mov_b32 vcc_lo, 0x00ff00ff
	s_mov_b32 vcc_hi, 0x00ff00ff
	v_cndmask_b32_dpp v244, v186, v174, vcc row_ror:8 row_mask:0xf bank_mask:0xf
	v_cndmask_b32_dpp v245, v187, v175, vcc row_ror:8 row_mask:0xf bank_mask:0xf
	v_cndmask_b32_dpp v246, v188, v176, vcc row_ror:8 row_mask:0xf bank_mask:0xf
	v_cndmask_b32_dpp v247, v189, v177, vcc row_ror:8 row_mask:0xf bank_mask:0xf
	s_mov_b32 s2, 0x8000
	s_mov_b32 s3, 0
	global_store_dwordx4 v[222:223], v[244:247], off sc1
	s_not_b64 vcc, vcc
	v_lshl_add_u64 v[222:223], v[222:223], 0, s[2:3]
	s_nop 0
	v_cndmask_b32_dpp v244, v174, v186, vcc row_ror:8 row_mask:0xf bank_mask:0xf
	v_cndmask_b32_dpp v245, v175, v187, vcc row_ror:8 row_mask:0xf bank_mask:0xf
	v_cndmask_b32_dpp v246, v176, v188, vcc row_ror:8 row_mask:0xf bank_mask:0xf
	v_cndmask_b32_dpp v247, v177, v189, vcc row_ror:8 row_mask:0xf bank_mask:0xf
	s_nop 0
	global_store_dwordx4 v[222:223], v[244:247], off sc1
	s_nop 1
	s_and_b64 vcc, exec, s[42:43]
	s_cbranch_vccz .LBB0_536
	v_bfe_u32 v244, v233, 4, 1
	v_mul_u32_u24_e32 v244, 24, v244
	v_mov_b32_e32 v245, 0
	v_lshl_add_u64 v[206:207], v[206:207], 0, v[244:245]
	v_cvt_pk_bf16_f32 v244, v174, v175
	v_cvt_pk_bf16_f32 v245, v176, v177
	v_cvt_pk_bf16_f32 v246, v186, v187
	v_cvt_pk_bf16_f32 v247, v188, v189
	s_nop 1
	v_permlane16_swap_b32_e32 v244, v246
	v_permlane16_swap_b32_e32 v245, v247
	s_nop 1
	global_store_dwordx4 v[206:207], v[244:247], off sc1
	s_nop 1
.LBB0_536:
	v_pk_add_f32 v[244:245], v[96:97], v[140:141]
	v_pk_add_f32 v[246:247], v[94:95], v[138:139]
	s_mov_b64 s[2:3], 0x200
	v_pk_fma_f32 v[164:165], v[244:245], s[94:95], v[164:165]
	v_pk_fma_f32 v[162:163], v[246:247], s[14:15], v[162:163]
	s_and_b64 vcc, exec, s[42:43]
	s_cbranch_vccz .LBB0_538
.LBB0_538:
	v_pk_add_f32 v[244:245], v[92:93], v[132:133]
	v_pk_add_f32 v[246:247], v[90:91], v[130:131]
	s_mov_b64 s[2:3], 0x240
	v_pk_fma_f32 v[152:153], v[244:245], s[94:95], v[152:153]
	v_pk_fma_f32 v[150:151], v[246:247], s[14:15], v[150:151]
	s_mov_b32 vcc_lo, 0xff00ff00
	s_mov_b32 vcc_hi, 0xff00ff00
	v_cndmask_b32_dpp v244, v162, v150, vcc row_ror:8 row_mask:0xf bank_mask:0xf
	v_cndmask_b32_dpp v245, v163, v151, vcc row_ror:8 row_mask:0xf bank_mask:0xf
	v_cndmask_b32_dpp v246, v164, v152, vcc row_ror:8 row_mask:0xf bank_mask:0xf
	v_cndmask_b32_dpp v247, v165, v153, vcc row_ror:8 row_mask:0xf bank_mask:0xf
	s_mov_b32 s2, 0xffff8000
	s_mov_b32 s3, -1
	global_store_dwordx4 v[222:223], v[244:247], off offset:512 sc1
	s_not_b64 vcc, vcc
	v_lshl_add_u64 v[222:223], v[222:223], 0, s[2:3]
	s_nop 0
	v_cndmask_b32_dpp v244, v150, v162, vcc row_ror:8 row_mask:0xf bank_mask:0xf
	v_cndmask_b32_dpp v245, v151, v163, vcc row_ror:8 row_mask:0xf bank_mask:0xf
	v_cndmask_b32_dpp v246, v152, v164, vcc row_ror:8 row_mask:0xf bank_mask:0xf
	v_cndmask_b32_dpp v247, v153, v165, vcc row_ror:8 row_mask:0xf bank_mask:0xf
	s_nop 0
	global_store_dwordx4 v[222:223], v[244:247], off offset:512 sc1
	s_nop 1
	s_and_b64 vcc, exec, s[42:43]
	s_cbranch_vccz .LBB0_540
	v_cvt_pk_bf16_f32 v244, v162, v163
	v_cvt_pk_bf16_f32 v245, v164, v165
	v_cvt_pk_bf16_f32 v246, v150, v151
	v_cvt_pk_bf16_f32 v247, v152, v153
	s_nop 1
	v_permlane16_swap_b32_e32 v244, v246
	v_permlane16_swap_b32_e32 v245, v247
	s_nop 1
	global_store_dwordx4 v[206:207], v[244:247], off offset:256 sc1
	s_nop 1

; __device__ __forceinline__ unsigned cvt_pk_bf16(float lo, float hi) { unsigned r; asm volatile("v_cvt_pk_bf16_f32 %0, %1, %2" : "=v"(r) : "v"(lo), "v"(hi)); return r; }
; __device__ __forceinline__ void st16f_wt(void* p, f32x4 v) { asm volatile("global_store_dwordx4 %0, %1, off sc1\n\ts_nop 1" :: "v"(p), "v"(v) : "memory"); }
; __device__ __forceinline__ void st8_wt(void* p, u32x2w v) { asm volatile("global_store_dwordx2 %0, %1, off sc1\n\ts_nop 1" :: "v"(p), "v"(v) : "memory"); }
;     __device__ __forceinline__ void operator()(const f32x4 (&acc)[2][2][4][2], const Unit& u, int wr, int wc, int fr, int fq) const {
;     ...
;         for (int gi = 0; gi < 8; ++gi) { const int ai = gi >> 2, m = gi & 3; const int row = row0 + ai * HALF + m * 16; const size_t off = (size_t)row * 1024 + col0; float s = 0.f;
;             if (gi < 6) { const int ai2 = (gi + 2) >> 2, m2 = (gi + 2) & 3; const int rr = row0 + ai2 * HALF + m2 * 16; const float* rb = Xin0 ? (rr < NP ? Xin0 + (size_t)rr * 1024 : Xin1 + (size_t)(rr - NP) * 1024) : X + (size_t)rr * 1024;
; #pragma unroll
;                 for (int bj = 0; bj < 2; ++bj)
; #pragma unroll
;                     for (int n = 0; n < 2; ++n) xr[(gi + 2) % 3][bj][n] = ld16f_ag(rb + col0 + bj * HALF + n * 16); }
;             f32x4 xc[2][2];
; #pragma unroll
;             for (int bj = 0; bj < 2; ++bj)
; #pragma unroll
;                 for (int n = 0; n < 2; ++n) xc[bj][n] = xr[gi % 3][bj][n];
;             if (gi == 0) publish_prev(pendp, lane, xc[1][1][3]);
; #pragma unroll
;             for (int bj = 0; bj < 2; ++bj)
; #pragma unroll
;                 for (int n = 0; n < 2; ++n) { f32x4 x = xc[bj][n] + (acc[ai][bj][m][n] + bv[bj][n]) * alpha; st16f_wt(X + off + bj * HALF + n * 16, x);
;                     if (XB) { u32x2w w; w.x = cvt_pk_bf16(x[0], x[1]); w.y = cvt_pk_bf16(x[2], x[3]); st8_wt(XB + off + bj * HALF + n * 16, w); }
.LBB0_552:
	s_waitcnt lgkmcnt(0)
	v_lshlrev_b64 v[150:151], 12, v[150:151]
	v_lshl_add_u64 v[150:151], v[152:153], 0, v[150:151]
	v_lshl_add_u64 v[150:151], v[150:151], 0, v[224:225]
	global_load_dwordx4 v[186:189], v[150:151], off
	global_load_dwordx4 v[174:177], v[150:151], off offset:64
	global_load_dwordx4 v[162:165], v[150:151], off offset:512
	s_nop 0
	global_load_dwordx4 v[150:153], v[150:151], off offset:576
	v_lshlrev_b64 v[206:207], 10, v[228:229]
	v_pk_add_f32 v[228:229], v[120:121], v[144:145]
	v_pk_add_f32 v[244:245], v[118:119], v[142:143]
	s_waitcnt vmcnt(11)
	v_pk_fma_f32 v[192:193], v[228:229], s[94:95], v[192:193]
	v_pk_fma_f32 v[190:191], v[244:245], s[14:15], v[190:191]
	v_lshl_add_u64 v[224:225], v[226:227], 0, v[224:225]
	v_lshl_add_u64 v[206:207], v[206:207], 0, v[218:219]
	s_and_b64 vcc, exec, s[42:43]
	v_lshl_add_u64 v[206:207], v[206:207], 1, s[88:89]
	s_cbranch_vccz .LBB0_554
.LBB0_554:
	v_pk_add_f32 v[226:227], v[116:117], v[136:137]
	v_pk_add_f32 v[228:229], v[114:115], v[134:135]
	s_waitcnt vmcnt(10)
	v_pk_fma_f32 v[180:181], v[226:227], s[94:95], v[180:181]
	v_pk_fma_f32 v[178:179], v[228:229], s[14:15], v[178:179]
	v_bfe_i32 v227, v233, 3, 1
	v_and_b32_e32 v226, 0xffff8040, v227
	v_lshl_add_u64 v[224:225], v[224:225], 0, v[226:227]
	s_mov_b32 vcc_lo, 0x00ff00ff
	s_mov_b32 vcc_hi, 0x00ff00ff
	v_cndmask_b32_dpp v226, v178, v190, vcc row_ror:8 row_mask:0xf bank_mask:0xf
	v_cndmask_b32_dpp v227, v179, v191, vcc row_ror:8 row_mask:0xf bank_mask:0xf
	v_cndmask_b32_dpp v228, v180, v192, vcc row_ror:8 row_mask:0xf bank_mask:0xf
	v_cndmask_b32_dpp v229, v181, v193, vcc row_ror:8 row_mask:0xf bank_mask:0xf
	s_mov_b32 s2, 0x8000
	s_mov_b32 s3, 0
	global_store_dwordx4 v[224:225], v[226:229], off sc1
	s_not_b64 vcc, vcc
	v_lshl_add_u64 v[224:225], v[224:225], 0, s[2:3]
	s_nop 0
	v_cndmask_b32_dpp v226, v190, v178, vcc row_ror:8 row_mask:0xf bank_mask:0xf
	v_cndmask_b32_dpp v227, v191, v179, vcc row_ror:8 row_mask:0xf bank_mask:0xf
	v_cndmask_b32_dpp v228, v192, v180, vcc row_ror:8 row_mask:0xf bank_mask:0xf
	v_cndmask_b32_dpp v229, v193, v181, vcc row_ror:8 row_mask:0xf bank_mask:0xf
	s_nop 0
	global_store_dwordx4 v[224:225], v[226:229], off sc1
	s_nop 1
	s_and_b64 vcc, exec, s[42:43]
	s_cbranch_vccz .LBB0_556
	v_bfe_u32 v226, v233, 4, 1
	v_mul_u32_u24_e32 v226, 24, v226
	v_mov_b32_e32 v227, 0
	v_lshl_add_u64 v[206:207], v[206:207], 0, v[226:227]
	v_cvt_pk_bf16_f32 v226, v190, v191
	v_cvt_pk_bf16_f32 v227, v192, v193
	v_cvt_pk_bf16_f32 v228, v178, v179
	v_cvt_pk_bf16_f32 v229, v180, v181
	s_nop 1
	v_permlane16_swap_b32_e32 v226, v228
	v_permlane16_swap_b32_e32 v227, v229
	s_nop 1
	global_store_dwordx4 v[206:207], v[226:229], off sc1
	s_nop 1
.LBB0_556:
	v_pk_add_f32 v[226:227], v[88:89], v[140:141]
	v_pk_add_f32 v[228:229], v[86:87], v[138:139]
	s_mov_b64 s[2:3], 0x200
	s_waitcnt vmcnt(9)
	v_pk_fma_f32 v[168:169], v[226:227], s[94:95], v[168:169]
	v_pk_fma_f32 v[166:167], v[228:229], s[14:15], v[166:167]
	s_and_b64 vcc, exec, s[42:43]
	s_cbranch_vccz .LBB0_558
.LBB0_558:
	v_pk_add_f32 v[226:227], v[84:85], v[132:133]
	v_pk_add_f32 v[228:229], v[82:83], v[130:131]
	s_mov_b64 s[2:3], 0x240
	s_waitcnt vmcnt(8)
	v_pk_fma_f32 v[156:157], v[226:227], s[94:95], v[156:157]
	v_pk_fma_f32 v[154:155], v[228:229], s[14:15], v[154:155]
	s_mov_b32 vcc_lo, 0xff00ff00
	s_mov_b32 vcc_hi, 0xff00ff00
	v_cndmask_b32_dpp v226, v166, v154, vcc row_ror:8 row_mask:0xf bank_mask:0xf
	v_cndmask_b32_dpp v227, v167, v155, vcc row_ror:8 row_mask:0xf bank_mask:0xf
	v_cndmask_b32_dpp v228, v168, v156, vcc row_ror:8 row_mask:0xf bank_mask:0xf
	v_cndmask_b32_dpp v229, v169, v157, vcc row_ror:8 row_mask:0xf bank_mask:0xf
	s_mov_b32 s2, 0xffff8000
	s_mov_b32 s3, -1
	global_store_dwordx4 v[224:225], v[226:229], off offset:512 sc1
	s_not_b64 vcc, vcc
	v_lshl_add_u64 v[224:225], v[224:225], 0, s[2:3]
	s_nop 0
	v_cndmask_b32_dpp v226, v154, v166, vcc row_ror:8 row_mask:0xf bank_mask:0xf
	v_cndmask_b32_dpp v227, v155, v167, vcc row_ror:8 row_mask:0xf bank_mask:0xf
	v_cndmask_b32_dpp v228, v156, v168, vcc row_ror:8 row_mask:0xf bank_mask:0xf
	v_cndmask_b32_dpp v229, v157, v169, vcc row_ror:8 row_mask:0xf bank_mask:0xf
	s_nop 0
	global_store_dwordx4 v[224:225], v[226:229], off offset:512 sc1
	s_nop 1
	s_and_b64 vcc, exec, s[42:43]
	s_cbranch_vccz .LBB0_560
	v_cvt_pk_bf16_f32 v226, v166, v167
	v_cvt_pk_bf16_f32 v227, v168, v169
	v_cvt_pk_bf16_f32 v228, v154, v155
	v_cvt_pk_bf16_f32 v229, v156, v157
	s_nop 1
	v_permlane16_swap_b32_e32 v226, v228
	v_permlane16_swap_b32_e32 v227, v229
	s_nop 1
	global_store_dwordx4 v[206:207], v[226:229], off offset:256 sc1
	s_nop 1

; __device__ __forceinline__ unsigned cvt_pk_bf16(float lo, float hi) { unsigned r; asm volatile("v_cvt_pk_bf16_f32 %0, %1, %2" : "=v"(r) : "v"(lo), "v"(hi)); return r; }
; __device__ __forceinline__ void st16f_wt(void* p, f32x4 v) { asm volatile("global_store_dwordx4 %0, %1, off sc1\n\ts_nop 1" :: "v"(p), "v"(v) : "memory"); }
; __device__ __forceinline__ void st8_wt(void* p, u32x2w v) { asm volatile("global_store_dwordx2 %0, %1, off sc1\n\ts_nop 1" :: "v"(p), "v"(v) : "memory"); }
;     __device__ __forceinline__ void operator()(const f32x4 (&acc)[2][2][4][2], const Unit& u, int wr, int wc, int fr, int fq) const {
;     ...
;         for (int gi = 0; gi < 8; ++gi) { const int ai = gi >> 2, m = gi & 3; const int row = row0 + ai * HALF + m * 16; const size_t off = (size_t)row * 1024 + col0; float s = 0.f;
;             if (gi < 6) { const int ai2 = (gi + 2) >> 2, m2 = (gi + 2) & 3; const int rr = row0 + ai2 * HALF + m2 * 16; const float* rb = Xin0 ? (rr < NP ? Xin0 + (size_t)rr * 1024 : Xin1 + (size_t)(rr - NP) * 1024) : X + (size_t)rr * 1024;
; #pragma unroll
;                 for (int bj = 0; bj < 2; ++bj)
; #pragma unroll
;                     for (int n = 0; n < 2; ++n) xr[(gi + 2) % 3][bj][n] = ld16f_ag(rb + col0 + bj * HALF + n * 16); }
;             f32x4 xc[2][2];
; #pragma unroll
;             for (int bj = 0; bj < 2; ++bj)
; #pragma unroll
;                 for (int n = 0; n < 2; ++n) xc[bj][n] = xr[gi % 3][bj][n];
;             if (gi == 0) publish_prev(pendp, lane, xc[1][1][3]);
; #pragma unroll
;             for (int bj = 0; bj < 2; ++bj)
; #pragma unroll
;                 for (int n = 0; n < 2; ++n) { f32x4 x = xc[bj][n] + (acc[ai][bj][m][n] + bv[bj][n]) * alpha; st16f_wt(X + off + bj * HALF + n * 16, x);
;                     if (XB) { u32x2w w; w.x = cvt_pk_bf16(x[0], x[1]); w.y = cvt_pk_bf16(x[2], x[3]); st8_wt(XB + off + bj * HALF + n * 16, w); }
;                     s += (x[0] * x[0] + x[1] * x[1]) + (x[2] * x[2] + x[3] * x[3]); }
.LBB0_572:
	s_waitcnt lgkmcnt(0)
	v_lshlrev_b64 v[154:155], 12, v[154:155]
	v_lshl_add_u64 v[154:155], v[156:157], 0, v[154:155]
	v_lshl_add_u64 v[154:155], v[218:219], 2, v[154:155]
	global_load_dwordx4 v[190:193], v[154:155], off
	global_load_dwordx4 v[178:181], v[154:155], off offset:64
	global_load_dwordx4 v[166:169], v[154:155], off offset:512
	s_nop 0
	global_load_dwordx4 v[154:157], v[154:155], off offset:576
	v_lshlrev_b64 v[220:221], 10, v[220:221]
	v_lshl_add_u64 v[220:221], v[220:221], 0, v[218:219]
	v_pk_add_f32 v[224:225], v[112:113], v[144:145]
	v_pk_add_f32 v[226:227], v[110:111], v[142:143]
	s_waitcnt vmcnt(11)
	v_pk_fma_f32 v[184:185], v[224:225], s[94:95], v[184:185]
	v_pk_fma_f32 v[182:183], v[226:227], s[14:15], v[182:183]
	v_lshl_add_u64 v[224:225], v[220:221], 2, s[68:69]
	s_and_b64 vcc, exec, s[42:43]
	v_lshl_add_u64 v[220:221], v[220:221], 1, s[88:89]
	s_cbranch_vccz .LBB0_574
.LBB0_574:
	v_pk_add_f32 v[226:227], v[108:109], v[136:137]
	v_pk_add_f32 v[228:229], v[106:107], v[134:135]
	s_waitcnt vmcnt(10)
	v_pk_fma_f32 v[172:173], v[226:227], s[94:95], v[172:173]
	v_pk_fma_f32 v[170:171], v[228:229], s[14:15], v[170:171]
	v_bfe_i32 v227, v233, 3, 1
	v_and_b32_e32 v226, 0xffff8040, v227
	v_lshl_add_u64 v[224:225], v[224:225], 0, v[226:227]
	s_mov_b32 vcc_lo, 0x00ff00ff
	s_mov_b32 vcc_hi, 0x00ff00ff
	v_cndmask_b32_dpp v226, v170, v182, vcc row_ror:8 row_mask:0xf bank_mask:0xf
	v_cndmask_b32_dpp v227, v171, v183, vcc row_ror:8 row_mask:0xf bank_mask:0xf
	v_cndmask_b32_dpp v228, v172, v184, vcc row_ror:8 row_mask:0xf bank_mask:0xf
	v_cndmask_b32_dpp v229, v173, v185, vcc row_ror:8 row_mask:0xf bank_mask:0xf
	s_mov_b32 s2, 0x8000
	s_mov_b32 s3, 0
	global_store_dwordx4 v[224:225], v[226:229], off sc1
	s_not_b64 vcc, vcc
	v_lshl_add_u64 v[224:225], v[224:225], 0, s[2:3]
	s_nop 0
	v_cndmask_b32_dpp v226, v182, v170, vcc row_ror:8 row_mask:0xf bank_mask:0xf
	v_cndmask_b32_dpp v227, v183, v171, vcc row_ror:8 row_mask:0xf bank_mask:0xf
	v_cndmask_b32_dpp v228, v184, v172, vcc row_ror:8 row_mask:0xf bank_mask:0xf
	v_cndmask_b32_dpp v229, v185, v173, vcc row_ror:8 row_mask:0xf bank_mask:0xf
	s_nop 0
	global_store_dwordx4 v[224:225], v[226:229], off sc1
	s_nop 1
	s_and_b64 vcc, exec, s[42:43]
	s_cbranch_vccz .LBB0_576
	v_bfe_u32 v226, v233, 4, 1
	v_mul_u32_u24_e32 v226, 24, v226
	v_mov_b32_e32 v227, 0
	v_lshl_add_u64 v[220:221], v[220:221], 0, v[226:227]
	v_cvt_pk_bf16_f32 v226, v182, v183
	v_cvt_pk_bf16_f32 v227, v184, v185
	v_cvt_pk_bf16_f32 v228, v170, v171
	v_cvt_pk_bf16_f32 v229, v172, v173
	s_nop 1
	v_permlane16_swap_b32_e32 v226, v228
	v_permlane16_swap_b32_e32 v227, v229
	s_nop 1
	global_store_dwordx4 v[220:221], v[226:229], off sc1
	s_nop 1
.LBB0_576:
	v_pk_add_f32 v[226:227], v[80:81], v[140:141]
	v_pk_add_f32 v[228:229], v[78:79], v[138:139]
	s_mov_b64 s[2:3], 0x200
	s_waitcnt vmcnt(9)
	v_pk_fma_f32 v[160:161], v[226:227], s[94:95], v[160:161]
	v_pk_fma_f32 v[158:159], v[228:229], s[14:15], v[158:159]
	s_and_b64 vcc, exec, s[42:43]
	s_cbranch_vccz .LBB0_578
.LBB0_578:
	v_pk_add_f32 v[226:227], v[76:77], v[132:133]
	v_pk_add_f32 v[228:229], v[74:75], v[130:131]
	s_mov_b64 s[2:3], 0x240
	s_waitcnt vmcnt(8)
	v_pk_fma_f32 v[148:149], v[226:227], s[94:95], v[148:149]
	v_pk_fma_f32 v[146:147], v[228:229], s[14:15], v[146:147]
	s_mov_b32 vcc_lo, 0xff00ff00
	s_mov_b32 vcc_hi, 0xff00ff00
	v_cndmask_b32_dpp v226, v158, v146, vcc row_ror:8 row_mask:0xf bank_mask:0xf
	v_cndmask_b32_dpp v227, v159, v147, vcc row_ror:8 row_mask:0xf bank_mask:0xf
	v_cndmask_b32_dpp v228, v160, v148, vcc row_ror:8 row_mask:0xf bank_mask:0xf
	v_cndmask_b32_dpp v229, v161, v149, vcc row_ror:8 row_mask:0xf bank_mask:0xf
	s_mov_b32 s2, 0xffff8000
	s_mov_b32 s3, -1
	global_store_dwordx4 v[224:225], v[226:229], off offset:512 sc1
	s_not_b64 vcc, vcc
	v_lshl_add_u64 v[224:225], v[224:225], 0, s[2:3]
	s_nop 0
	v_cndmask_b32_dpp v226, v146, v158, vcc row_ror:8 row_mask:0xf bank_mask:0xf
	v_cndmask_b32_dpp v227, v147, v159, vcc row_ror:8 row_mask:0xf bank_mask:0xf
	v_cndmask_b32_dpp v228, v148, v160, vcc row_ror:8 row_mask:0xf bank_mask:0xf
	v_cndmask_b32_dpp v229, v149, v161, vcc row_ror:8 row_mask:0xf bank_mask:0xf
	s_nop 0
	global_store_dwordx4 v[224:225], v[226:229], off offset:512 sc1
	s_nop 1
	s_and_b64 vcc, exec, s[42:43]
	s_cbranch_vccz .LBB0_580
	v_cvt_pk_bf16_f32 v226, v158, v159
	v_cvt_pk_bf16_f32 v227, v160, v161
	v_cvt_pk_bf16_f32 v228, v146, v147
	v_cvt_pk_bf16_f32 v229, v148, v149
	s_nop 1
	v_permlane16_swap_b32_e32 v226, v228
	v_permlane16_swap_b32_e32 v227, v229
	s_nop 1
	global_store_dwordx4 v[220:221], v[226:229], off offset:256 sc1
	s_nop 1

; __device__ __forceinline__ unsigned cvt_pk_bf16(float lo, float hi) { unsigned r; asm volatile("v_cvt_pk_bf16_f32 %0, %1, %2" : "=v"(r) : "v"(lo), "v"(hi)); return r; }
; __device__ __forceinline__ void st16f_wt(void* p, f32x4 v) { asm volatile("global_store_dwordx4 %0, %1, off sc1\n\ts_nop 1" :: "v"(p), "v"(v) : "memory"); }
; __device__ __forceinline__ void st8_wt(void* p, u32x2w v) { asm volatile("global_store_dwordx2 %0, %1, off sc1\n\ts_nop 1" :: "v"(p), "v"(v) : "memory"); }
;     __device__ __forceinline__ void operator()(const f32x4 (&acc)[2][2][4][2], const Unit& u, int wr, int wc, int fr, int fq) const {
;     ...
;         for (int gi = 0; gi < 8; ++gi) { const int ai = gi >> 2, m = gi & 3; const int row = row0 + ai * HALF + m * 16; const size_t off = (size_t)row * 1024 + col0; float s = 0.f;
;             if (gi < 6) { const int ai2 = (gi + 2) >> 2, m2 = (gi + 2) & 3; const int rr = row0 + ai2 * HALF + m2 * 16; const float* rb = Xin0 ? (rr < NP ? Xin0 + (size_t)rr * 1024 : Xin1 + (size_t)(rr - NP) * 1024) : X + (size_t)rr * 1024;
; #pragma unroll
;                 for (int bj = 0; bj < 2; ++bj)
; #pragma unroll
;                     for (int n = 0; n < 2; ++n) xr[(gi + 2) % 3][bj][n] = ld16f_ag(rb + col0 + bj * HALF + n * 16); }
;             f32x4 xc[2][2];
; #pragma unroll
;             for (int bj = 0; bj < 2; ++bj)
; #pragma unroll
;                 for (int n = 0; n < 2; ++n) xc[bj][n] = xr[gi % 3][bj][n];
;             if (gi == 0) publish_prev(pendp, lane, xc[1][1][3]);
; #pragma unroll
;             for (int bj = 0; bj < 2; ++bj)
; #pragma unroll
;                 for (int n = 0; n < 2; ++n) { f32x4 x = xc[bj][n] + (acc[ai][bj][m][n] + bv[bj][n]) * alpha; st16f_wt(X + off + bj * HALF + n * 16, x);
;                     if (XB) { u32x2w w; w.x = cvt_pk_bf16(x[0], x[1]); w.y = cvt_pk_bf16(x[2], x[3]); st8_wt(XB + off + bj * HALF + n * 16, w); }
;                     s += (x[0] * x[0] + x[1] * x[1]) + (x[2] * x[2] + x[3] * x[3]); }
.LBB0_592:
	s_waitcnt lgkmcnt(0)
	v_lshlrev_b64 v[146:147], 12, v[148:149]
	v_lshl_add_u64 v[146:147], v[158:159], 0, v[146:147]
	v_lshl_add_u64 v[146:147], v[218:219], 2, v[146:147]
	global_load_dwordx4 v[182:185], v[146:147], off
	global_load_dwordx4 v[170:173], v[146:147], off offset:64
	global_load_dwordx4 v[158:161], v[146:147], off offset:512
	s_nop 0
	global_load_dwordx4 v[146:149], v[146:147], off offset:576
	v_lshlrev_b64 v[220:221], 10, v[222:223]
	v_lshl_add_u64 v[220:221], v[220:221], 0, v[218:219]
	v_pk_add_f32 v[222:223], v[104:105], v[144:145]
	v_pk_add_f32 v[224:225], v[102:103], v[142:143]
	s_waitcnt vmcnt(11)
	v_pk_fma_f32 v[188:189], v[222:223], s[94:95], v[188:189]
	v_pk_fma_f32 v[186:187], v[224:225], s[14:15], v[186:187]
	v_lshl_add_u64 v[222:223], v[220:221], 2, s[68:69]
	s_and_b64 vcc, exec, s[42:43]
	v_lshl_add_u64 v[220:221], v[220:221], 1, s[88:89]
	s_cbranch_vccz .LBB0_594
.LBB0_594:
	v_pk_add_f32 v[224:225], v[100:101], v[136:137]
	v_pk_add_f32 v[226:227], v[98:99], v[134:135]
	s_waitcnt vmcnt(10)
	v_pk_fma_f32 v[176:177], v[224:225], s[94:95], v[176:177]
	v_pk_fma_f32 v[174:175], v[226:227], s[14:15], v[174:175]
	v_bfe_i32 v225, v233, 3, 1
	v_and_b32_e32 v224, 0xffff8040, v225
	v_lshl_add_u64 v[222:223], v[222:223], 0, v[224:225]
	s_mov_b32 vcc_lo, 0x00ff00ff
	s_mov_b32 vcc_hi, 0x00ff00ff
	v_cndmask_b32_dpp v224, v174, v186, vcc row_ror:8 row_mask:0xf bank_mask:0xf
	v_cndmask_b32_dpp v225, v175, v187, vcc row_ror:8 row_mask:0xf bank_mask:0xf
	v_cndmask_b32_dpp v226, v176, v188, vcc row_ror:8 row_mask:0xf bank_mask:0xf
	v_cndmask_b32_dpp v227, v177, v189, vcc row_ror:8 row_mask:0xf bank_mask:0xf
	s_mov_b32 s2, 0x8000
	s_mov_b32 s3, 0
	global_store_dwordx4 v[222:223], v[224:227], off sc1
	s_not_b64 vcc, vcc
	v_lshl_add_u64 v[222:223], v[222:223], 0, s[2:3]
	s_nop 0
	v_cndmask_b32_dpp v224, v186, v174, vcc row_ror:8 row_mask:0xf bank_mask:0xf
	v_cndmask_b32_dpp v225, v187, v175, vcc row_ror:8 row_mask:0xf bank_mask:0xf
	v_cndmask_b32_dpp v226, v188, v176, vcc row_ror:8 row_mask:0xf bank_mask:0xf
	v_cndmask_b32_dpp v227, v189, v177, vcc row_ror:8 row_mask:0xf bank_mask:0xf
	s_nop 0
	global_store_dwordx4 v[222:223], v[224:227], off sc1
	s_nop 1
	s_and_b64 vcc, exec, s[42:43]
	s_cbranch_vccz .LBB0_596
	v_bfe_u32 v224, v233, 4, 1
	v_mul_u32_u24_e32 v224, 24, v224
	v_mov_b32_e32 v225, 0
	v_lshl_add_u64 v[220:221], v[220:221], 0, v[224:225]
	v_cvt_pk_bf16_f32 v224, v186, v187
	v_cvt_pk_bf16_f32 v225, v188, v189
	v_cvt_pk_bf16_f32 v226, v174, v175
	v_cvt_pk_bf16_f32 v227, v176, v177
	s_nop 1
	v_permlane16_swap_b32_e32 v224, v226
	v_permlane16_swap_b32_e32 v225, v227
	s_nop 1
	global_store_dwordx4 v[220:221], v[224:227], off sc1
	s_nop 1
.LBB0_596:
	v_pk_add_f32 v[224:225], v[72:73], v[140:141]
	v_pk_add_f32 v[226:227], v[70:71], v[138:139]
	s_mov_b64 s[2:3], 0x200
	s_waitcnt vmcnt(9)
	v_pk_fma_f32 v[164:165], v[224:225], s[94:95], v[164:165]
	v_pk_fma_f32 v[162:163], v[226:227], s[14:15], v[162:163]
	s_and_b64 vcc, exec, s[42:43]
	s_cbranch_vccz .LBB0_598
.LBB0_598:
	v_pk_add_f32 v[224:225], v[68:69], v[132:133]
	v_pk_add_f32 v[226:227], v[66:67], v[130:131]
	s_mov_b64 s[2:3], 0x240
	s_waitcnt vmcnt(8)
	v_pk_fma_f32 v[152:153], v[224:225], s[94:95], v[152:153]
	v_pk_fma_f32 v[150:151], v[226:227], s[14:15], v[150:151]
	s_mov_b32 vcc_lo, 0xff00ff00
	s_mov_b32 vcc_hi, 0xff00ff00
	v_cndmask_b32_dpp v224, v162, v150, vcc row_ror:8 row_mask:0xf bank_mask:0xf
	v_cndmask_b32_dpp v225, v163, v151, vcc row_ror:8 row_mask:0xf bank_mask:0xf
	v_cndmask_b32_dpp v226, v164, v152, vcc row_ror:8 row_mask:0xf bank_mask:0xf
	v_cndmask_b32_dpp v227, v165, v153, vcc row_ror:8 row_mask:0xf bank_mask:0xf
	s_mov_b32 s2, 0xffff8000
	s_mov_b32 s3, -1
	global_store_dwordx4 v[222:223], v[224:227], off offset:512 sc1
	s_not_b64 vcc, vcc
	v_lshl_add_u64 v[222:223], v[222:223], 0, s[2:3]
	s_nop 0
	v_cndmask_b32_dpp v224, v150, v162, vcc row_ror:8 row_mask:0xf bank_mask:0xf
	v_cndmask_b32_dpp v225, v151, v163, vcc row_ror:8 row_mask:0xf bank_mask:0xf
	v_cndmask_b32_dpp v226, v152, v164, vcc row_ror:8 row_mask:0xf bank_mask:0xf
	v_cndmask_b32_dpp v227, v153, v165, vcc row_ror:8 row_mask:0xf bank_mask:0xf
	s_nop 0
	global_store_dwordx4 v[222:223], v[224:227], off offset:512 sc1
	s_nop 1
	s_and_b64 vcc, exec, s[42:43]
	s_cbranch_vccz .LBB0_600
	v_cvt_pk_bf16_f32 v224, v162, v163
	v_cvt_pk_bf16_f32 v225, v164, v165
	v_cvt_pk_bf16_f32 v226, v150, v151
	v_cvt_pk_bf16_f32 v227, v152, v153
	s_nop 1
	v_permlane16_swap_b32_e32 v224, v226
	v_permlane16_swap_b32_e32 v225, v227
	s_nop 1
	global_store_dwordx4 v[220:221], v[224:227], off offset:256 sc1
	s_nop 1

; __device__ __forceinline__ unsigned cvt_pk_bf16(float lo, float hi) { unsigned r; asm volatile("v_cvt_pk_bf16_f32 %0, %1, %2" : "=v"(r) : "v"(lo), "v"(hi)); return r; }
; __device__ __forceinline__ void st16f_wt(void* p, f32x4 v) { asm volatile("global_store_dwordx4 %0, %1, off sc1\n\ts_nop 1" :: "v"(p), "v"(v) : "memory"); }
; __device__ __forceinline__ void st8_wt(void* p, u32x2w v) { asm volatile("global_store_dwordx2 %0, %1, off sc1\n\ts_nop 1" :: "v"(p), "v"(v) : "memory"); }
;     __device__ __forceinline__ void operator()(const f32x4 (&acc)[2][2][4][2], const Unit& u, int wr, int wc, int fr, int fq) const {
;     ...
;         for (int gi = 0; gi < 8; ++gi) { const int ai = gi >> 2, m = gi & 3; const int row = row0 + ai * HALF + m * 16; const size_t off = (size_t)row * 1024 + col0; float s = 0.f;
;             if (gi < 6) { const int ai2 = (gi + 2) >> 2, m2 = (gi + 2) & 3; const int rr = row0 + ai2 * HALF + m2 * 16; const float* rb = Xin0 ? (rr < NP ? Xin0 + (size_t)rr * 1024 : Xin1 + (size_t)(rr - NP) * 1024) : X + (size_t)rr * 1024;
; #pragma unroll
;                 for (int bj = 0; bj < 2; ++bj)
; #pragma unroll
;                     for (int n = 0; n < 2; ++n) xr[(gi + 2) % 3][bj][n] = ld16f_ag(rb + col0 + bj * HALF + n * 16); }
;             f32x4 xc[2][2];
; #pragma unroll
;             for (int bj = 0; bj < 2; ++bj)
; #pragma unroll
;                 for (int n = 0; n < 2; ++n) xc[bj][n] = xr[gi % 3][bj][n];
;             if (gi == 0) publish_prev(pendp, lane, xc[1][1][3]);
; #pragma unroll
;             for (int bj = 0; bj < 2; ++bj)
; #pragma unroll
;                 for (int n = 0; n < 2; ++n) { f32x4 x = xc[bj][n] + (acc[ai][bj][m][n] + bv[bj][n]) * alpha; st16f_wt(X + off + bj * HALF + n * 16, x);
;                     if (XB) { u32x2w w; w.x = cvt_pk_bf16(x[0], x[1]); w.y = cvt_pk_bf16(x[2], x[3]); st8_wt(XB + off + bj * HALF + n * 16, w); }
;                     s += (x[0] * x[0] + x[1] * x[1]) + (x[2] * x[2] + x[3] * x[3]); }
.LBB0_612:
	s_waitcnt lgkmcnt(0)
	v_lshlrev_b64 v[150:151], 12, v[150:151]
	v_lshl_add_u64 v[150:151], v[152:153], 0, v[150:151]
	v_lshl_add_u64 v[150:151], v[218:219], 2, v[150:151]
	global_load_dwordx4 v[186:189], v[150:151], off
	global_load_dwordx4 v[174:177], v[150:151], off offset:64
	global_load_dwordx4 v[162:165], v[150:151], off offset:512
	s_nop 0
	global_load_dwordx4 v[150:153], v[150:151], off offset:576
	v_lshlrev_b64 v[222:223], 10, v[206:207]
	v_lshl_add_u64 v[222:223], v[222:223], 0, v[218:219]
	v_pk_add_f32 v[224:225], v[64:65], v[144:145]
	v_pk_add_f32 v[226:227], v[62:63], v[142:143]
	s_waitcnt vmcnt(11)
	v_pk_fma_f32 v[192:193], v[224:225], s[94:95], v[192:193]
	v_pk_fma_f32 v[190:191], v[226:227], s[14:15], v[190:191]
	v_lshl_add_u64 v[224:225], v[222:223], 2, s[68:69]
	s_and_b64 vcc, exec, s[42:43]
	v_lshl_add_u64 v[222:223], v[222:223], 1, s[88:89]
	s_cbranch_vccz .LBB0_614
.LBB0_614:
	v_pk_add_f32 v[226:227], v[60:61], v[136:137]
	v_pk_add_f32 v[228:229], v[58:59], v[134:135]
	s_waitcnt vmcnt(10)
	v_pk_fma_f32 v[180:181], v[226:227], s[94:95], v[180:181]
	v_pk_fma_f32 v[178:179], v[228:229], s[14:15], v[178:179]
	v_bfe_i32 v227, v233, 3, 1
	v_and_b32_e32 v226, 0xffff8040, v227
	v_lshl_add_u64 v[224:225], v[224:225], 0, v[226:227]
	s_mov_b32 vcc_lo, 0x00ff00ff
	s_mov_b32 vcc_hi, 0x00ff00ff
	v_cndmask_b32_dpp v226, v178, v190, vcc row_ror:8 row_mask:0xf bank_mask:0xf
	v_cndmask_b32_dpp v227, v179, v191, vcc row_ror:8 row_mask:0xf bank_mask:0xf
	v_cndmask_b32_dpp v228, v180, v192, vcc row_ror:8 row_mask:0xf bank_mask:0xf
	v_cndmask_b32_dpp v229, v181, v193, vcc row_ror:8 row_mask:0xf bank_mask:0xf
	s_mov_b32 s2, 0x8000
	s_mov_b32 s3, 0
	global_store_dwordx4 v[224:225], v[226:229], off sc1
	s_not_b64 vcc, vcc
	v_lshl_add_u64 v[224:225], v[224:225], 0, s[2:3]
	s_nop 0
	v_cndmask_b32_dpp v226, v190, v178, vcc row_ror:8 row_mask:0xf bank_mask:0xf
	v_cndmask_b32_dpp v227, v191, v179, vcc row_ror:8 row_mask:0xf bank_mask:0xf
	v_cndmask_b32_dpp v228, v192, v180, vcc row_ror:8 row_mask:0xf bank_mask:0xf
	v_cndmask_b32_dpp v229, v193, v181, vcc row_ror:8 row_mask:0xf bank_mask:0xf
	s_nop 0
	global_store_dwordx4 v[224:225], v[226:229], off sc1
	s_nop 1
	s_and_b64 vcc, exec, s[42:43]
	s_cbranch_vccz .LBB0_616
	v_bfe_u32 v226, v233, 4, 1
	v_mul_u32_u24_e32 v226, 24, v226
	v_mov_b32_e32 v227, 0
	v_lshl_add_u64 v[222:223], v[222:223], 0, v[226:227]
	v_cvt_pk_bf16_f32 v226, v190, v191
	v_cvt_pk_bf16_f32 v227, v192, v193
	v_cvt_pk_bf16_f32 v228, v178, v179
	v_cvt_pk_bf16_f32 v229, v180, v181
	s_nop 1
	v_permlane16_swap_b32_e32 v226, v228
	v_permlane16_swap_b32_e32 v227, v229
	s_nop 1
	global_store_dwordx4 v[222:223], v[226:229], off sc1
	s_nop 1
.LBB0_616:
	v_pk_add_f32 v[226:227], v[32:33], v[140:141]
	v_pk_add_f32 v[228:229], v[30:31], v[138:139]
	s_mov_b64 s[2:3], 0x200
	s_waitcnt vmcnt(9)
	v_pk_fma_f32 v[168:169], v[226:227], s[94:95], v[168:169]
	v_pk_fma_f32 v[166:167], v[228:229], s[14:15], v[166:167]
	s_and_b64 vcc, exec, s[42:43]
	s_cbranch_vccz .LBB0_618
.LBB0_618:
	v_pk_add_f32 v[226:227], v[28:29], v[132:133]
	v_pk_add_f32 v[228:229], v[26:27], v[130:131]
	s_mov_b64 s[2:3], 0x240
	s_waitcnt vmcnt(8)
	v_pk_fma_f32 v[156:157], v[226:227], s[94:95], v[156:157]
	v_pk_fma_f32 v[154:155], v[228:229], s[14:15], v[154:155]
	s_mov_b32 vcc_lo, 0xff00ff00
	s_mov_b32 vcc_hi, 0xff00ff00
	v_cndmask_b32_dpp v226, v166, v154, vcc row_ror:8 row_mask:0xf bank_mask:0xf
	v_cndmask_b32_dpp v227, v167, v155, vcc row_ror:8 row_mask:0xf bank_mask:0xf
	v_cndmask_b32_dpp v228, v168, v156, vcc row_ror:8 row_mask:0xf bank_mask:0xf
	v_cndmask_b32_dpp v229, v169, v157, vcc row_ror:8 row_mask:0xf bank_mask:0xf
	s_mov_b32 s2, 0xffff8000
	s_mov_b32 s3, -1
	global_store_dwordx4 v[224:225], v[226:229], off offset:512 sc1
	s_not_b64 vcc, vcc
	v_lshl_add_u64 v[224:225], v[224:225], 0, s[2:3]
	s_nop 0
	v_cndmask_b32_dpp v226, v154, v166, vcc row_ror:8 row_mask:0xf bank_mask:0xf
	v_cndmask_b32_dpp v227, v155, v167, vcc row_ror:8 row_mask:0xf bank_mask:0xf
	v_cndmask_b32_dpp v228, v156, v168, vcc row_ror:8 row_mask:0xf bank_mask:0xf
	v_cndmask_b32_dpp v229, v157, v169, vcc row_ror:8 row_mask:0xf bank_mask:0xf
	s_nop 0
	global_store_dwordx4 v[224:225], v[226:229], off offset:512 sc1
	s_nop 1
	s_and_b64 vcc, exec, s[42:43]
	s_cbranch_vccz .LBB0_620
	v_cvt_pk_bf16_f32 v226, v166, v167
	v_cvt_pk_bf16_f32 v227, v168, v169
	v_cvt_pk_bf16_f32 v228, v154, v155
	v_cvt_pk_bf16_f32 v229, v156, v157
	s_nop 1
	v_permlane16_swap_b32_e32 v226, v228
	v_permlane16_swap_b32_e32 v227, v229
	s_nop 1
	global_store_dwordx4 v[222:223], v[226:229], off offset:256 sc1
	s_nop 1

; __device__ __forceinline__ unsigned cvt_pk_bf16(float lo, float hi) { unsigned r; asm volatile("v_cvt_pk_bf16_f32 %0, %1, %2" : "=v"(r) : "v"(lo), "v"(hi)); return r; }
; __device__ __forceinline__ void st16f_wt(void* p, f32x4 v) { asm volatile("global_store_dwordx4 %0, %1, off sc1\n\ts_nop 1" :: "v"(p), "v"(v) : "memory"); }
; __device__ __forceinline__ void st8_wt(void* p, u32x2w v) { asm volatile("global_store_dwordx2 %0, %1, off sc1\n\ts_nop 1" :: "v"(p), "v"(v) : "memory"); }
;     __device__ __forceinline__ void operator()(const f32x4 (&acc)[2][2][4][2], const Unit& u, int wr, int wc, int fr, int fq) const {
;     ...
;         for (int gi = 0; gi < 8; ++gi) { const int ai = gi >> 2, m = gi & 3; const int row = row0 + ai * HALF + m * 16; const size_t off = (size_t)row * 1024 + col0; float s = 0.f;
;             if (gi < 6) { const int ai2 = (gi + 2) >> 2, m2 = (gi + 2) & 3; const int rr = row0 + ai2 * HALF + m2 * 16; const float* rb = Xin0 ? (rr < NP ? Xin0 + (size_t)rr * 1024 : Xin1 + (size_t)(rr - NP) * 1024) : X + (size_t)rr * 1024;
; #pragma unroll
;                 for (int bj = 0; bj < 2; ++bj)
; #pragma unroll
;                     for (int n = 0; n < 2; ++n) xr[(gi + 2) % 3][bj][n] = ld16f_ag(rb + col0 + bj * HALF + n * 16); }
;             f32x4 xc[2][2];
; #pragma unroll
;             for (int bj = 0; bj < 2; ++bj)
; #pragma unroll
;                 for (int n = 0; n < 2; ++n) xc[bj][n] = xr[gi % 3][bj][n];
;             if (gi == 0) publish_prev(pendp, lane, xc[1][1][3]);
; #pragma unroll
;             for (int bj = 0; bj < 2; ++bj)
; #pragma unroll
;                 for (int n = 0; n < 2; ++n) { f32x4 x = xc[bj][n] + (acc[ai][bj][m][n] + bv[bj][n]) * alpha; st16f_wt(X + off + bj * HALF + n * 16, x);
;                     if (XB) { u32x2w w; w.x = cvt_pk_bf16(x[0], x[1]); w.y = cvt_pk_bf16(x[2], x[3]); st8_wt(XB + off + bj * HALF + n * 16, w); }
;                     s += (x[0] * x[0] + x[1] * x[1]) + (x[2] * x[2] + x[3] * x[3]); }
.LBB0_632:
	s_waitcnt lgkmcnt(0)
	v_lshlrev_b64 v[154:155], 12, v[154:155]
	v_lshl_add_u64 v[154:155], v[156:157], 0, v[154:155]
	v_lshl_add_u64 v[154:155], v[218:219], 2, v[154:155]
	global_load_dwordx4 v[190:193], v[154:155], off
	global_load_dwordx4 v[178:181], v[154:155], off offset:64
	global_load_dwordx4 v[166:169], v[154:155], off offset:512
	s_nop 0
	global_load_dwordx4 v[154:157], v[154:155], off offset:576
	v_or_b32_e32 v206, 16, v206
	v_ashrrev_i32_e32 v207, 31, v206
	v_lshlrev_b64 v[206:207], 10, v[206:207]
	v_lshl_add_u64 v[206:207], v[206:207], 0, v[218:219]
	v_pk_add_f32 v[224:225], v[56:57], v[144:145]
	v_pk_add_f32 v[226:227], v[54:55], v[142:143]
	s_waitcnt vmcnt(11)
	v_pk_fma_f32 v[184:185], v[224:225], s[94:95], v[184:185]
	v_pk_fma_f32 v[182:183], v[226:227], s[14:15], v[182:183]
	v_lshl_add_u64 v[224:225], v[206:207], 2, s[68:69]
	s_and_b64 vcc, exec, s[42:43]
	v_lshl_add_u64 v[206:207], v[206:207], 1, s[88:89]
	s_cbranch_vccz .LBB0_634
.LBB0_634:
	v_pk_add_f32 v[226:227], v[52:53], v[136:137]
	v_pk_add_f32 v[228:229], v[50:51], v[134:135]
	s_waitcnt vmcnt(10)
	v_pk_fma_f32 v[172:173], v[226:227], s[94:95], v[172:173]
	v_pk_fma_f32 v[170:171], v[228:229], s[14:15], v[170:171]
	v_bfe_i32 v227, v233, 3, 1
	v_and_b32_e32 v226, 0xffff8040, v227
	v_lshl_add_u64 v[224:225], v[224:225], 0, v[226:227]
	s_mov_b32 vcc_lo, 0x00ff00ff
	s_mov_b32 vcc_hi, 0x00ff00ff
	v_cndmask_b32_dpp v226, v170, v182, vcc row_ror:8 row_mask:0xf bank_mask:0xf
	v_cndmask_b32_dpp v227, v171, v183, vcc row_ror:8 row_mask:0xf bank_mask:0xf
	v_cndmask_b32_dpp v228, v172, v184, vcc row_ror:8 row_mask:0xf bank_mask:0xf
	v_cndmask_b32_dpp v229, v173, v185, vcc row_ror:8 row_mask:0xf bank_mask:0xf
	s_mov_b32 s2, 0x8000
	s_mov_b32 s3, 0
	global_store_dwordx4 v[224:225], v[226:229], off sc1
	s_not_b64 vcc, vcc
	v_lshl_add_u64 v[224:225], v[224:225], 0, s[2:3]
	s_nop 0
	v_cndmask_b32_dpp v226, v182, v170, vcc row_ror:8 row_mask:0xf bank_mask:0xf
	v_cndmask_b32_dpp v227, v183, v171, vcc row_ror:8 row_mask:0xf bank_mask:0xf
	v_cndmask_b32_dpp v228, v184, v172, vcc row_ror:8 row_mask:0xf bank_mask:0xf
	v_cndmask_b32_dpp v229, v185, v173, vcc row_ror:8 row_mask:0xf bank_mask:0xf
	s_nop 0
	global_store_dwordx4 v[224:225], v[226:229], off sc1
	s_nop 1
	s_and_b64 vcc, exec, s[42:43]
	s_cbranch_vccz .LBB0_636
	v_bfe_u32 v226, v233, 4, 1
	v_mul_u32_u24_e32 v226, 24, v226
	v_mov_b32_e32 v227, 0
	v_lshl_add_u64 v[206:207], v[206:207], 0, v[226:227]
	v_cvt_pk_bf16_f32 v226, v182, v183
	v_cvt_pk_bf16_f32 v227, v184, v185
	v_cvt_pk_bf16_f32 v228, v170, v171
	v_cvt_pk_bf16_f32 v229, v172, v173
	s_nop 1
	v_permlane16_swap_b32_e32 v226, v228
	v_permlane16_swap_b32_e32 v227, v229
	s_nop 1
	global_store_dwordx4 v[206:207], v[226:229], off sc1
	s_nop 1
.LBB0_636:
	v_pk_add_f32 v[226:227], v[24:25], v[140:141]
	v_pk_add_f32 v[228:229], v[22:23], v[138:139]
	s_mov_b64 s[2:3], 0x200
	s_waitcnt vmcnt(9)
	v_pk_fma_f32 v[160:161], v[226:227], s[94:95], v[160:161]
	v_pk_fma_f32 v[158:159], v[228:229], s[14:15], v[158:159]
	s_and_b64 vcc, exec, s[42:43]
	s_cbranch_vccz .LBB0_638
.LBB0_638:
	v_pk_add_f32 v[226:227], v[20:21], v[132:133]
	v_pk_add_f32 v[228:229], v[18:19], v[130:131]
	s_mov_b64 s[2:3], 0x240
	s_waitcnt vmcnt(8)
	v_pk_fma_f32 v[148:149], v[226:227], s[94:95], v[148:149]
	v_pk_fma_f32 v[146:147], v[228:229], s[14:15], v[146:147]
	s_mov_b32 vcc_lo, 0xff00ff00
	s_mov_b32 vcc_hi, 0xff00ff00
	v_cndmask_b32_dpp v226, v158, v146, vcc row_ror:8 row_mask:0xf bank_mask:0xf
	v_cndmask_b32_dpp v227, v159, v147, vcc row_ror:8 row_mask:0xf bank_mask:0xf
	v_cndmask_b32_dpp v228, v160, v148, vcc row_ror:8 row_mask:0xf bank_mask:0xf
	v_cndmask_b32_dpp v229, v161, v149, vcc row_ror:8 row_mask:0xf bank_mask:0xf
	s_mov_b32 s2, 0xffff8000
	s_mov_b32 s3, -1
	global_store_dwordx4 v[224:225], v[226:229], off offset:512 sc1
	s_not_b64 vcc, vcc
	v_lshl_add_u64 v[224:225], v[224:225], 0, s[2:3]
	s_nop 0
	v_cndmask_b32_dpp v226, v146, v158, vcc row_ror:8 row_mask:0xf bank_mask:0xf
	v_cndmask_b32_dpp v227, v147, v159, vcc row_ror:8 row_mask:0xf bank_mask:0xf
	v_cndmask_b32_dpp v228, v148, v160, vcc row_ror:8 row_mask:0xf bank_mask:0xf
	v_cndmask_b32_dpp v229, v149, v161, vcc row_ror:8 row_mask:0xf bank_mask:0xf
	s_nop 0
	global_store_dwordx4 v[224:225], v[226:229], off offset:512 sc1
	s_nop 1
	s_and_b64 vcc, exec, s[42:43]
	s_cbranch_vccz .LBB0_640
	v_cvt_pk_bf16_f32 v226, v158, v159
	v_cvt_pk_bf16_f32 v227, v160, v161
	v_cvt_pk_bf16_f32 v228, v146, v147
	v_cvt_pk_bf16_f32 v229, v148, v149
	s_nop 1
	v_permlane16_swap_b32_e32 v226, v228
	v_permlane16_swap_b32_e32 v227, v229
	s_nop 1
	global_store_dwordx4 v[206:207], v[226:229], off offset:256 sc1
	s_nop 1

; __device__ __forceinline__ unsigned cvt_pk_bf16(float lo, float hi) { unsigned r; asm volatile("v_cvt_pk_bf16_f32 %0, %1, %2" : "=v"(r) : "v"(lo), "v"(hi)); return r; }
; __device__ __forceinline__ void st16f_wt(void* p, f32x4 v) { asm volatile("global_store_dwordx4 %0, %1, off sc1\n\ts_nop 1" :: "v"(p), "v"(v) : "memory"); }
; __device__ __forceinline__ void st8_wt(void* p, u32x2w v) { asm volatile("global_store_dwordx2 %0, %1, off sc1\n\ts_nop 1" :: "v"(p), "v"(v) : "memory"); }
;     __device__ __forceinline__ void operator()(const f32x4 (&acc)[2][2][4][2], const Unit& u, int wr, int wc, int fr, int fq) const {
;     ...
;         for (int gi = 0; gi < 8; ++gi) { const int ai = gi >> 2, m = gi & 3; const int row = row0 + ai * HALF + m * 16; const size_t off = (size_t)row * 1024 + col0; float s = 0.f;
;             if (gi < 6) { const int ai2 = (gi + 2) >> 2, m2 = (gi + 2) & 3; const int rr = row0 + ai2 * HALF + m2 * 16; const float* rb = Xin0 ? (rr < NP ? Xin0 + (size_t)rr * 1024 : Xin1 + (size_t)(rr - NP) * 1024) : X + (size_t)rr * 1024;
; #pragma unroll
;                 for (int bj = 0; bj < 2; ++bj)
; #pragma unroll
;                     for (int n = 0; n < 2; ++n) xr[(gi + 2) % 3][bj][n] = ld16f_ag(rb + col0 + bj * HALF + n * 16); }
;             f32x4 xc[2][2];
; #pragma unroll
;             for (int bj = 0; bj < 2; ++bj)
; #pragma unroll
;                 for (int n = 0; n < 2; ++n) xc[bj][n] = xr[gi % 3][bj][n];
;             if (gi == 0) publish_prev(pendp, lane, xc[1][1][3]);
; #pragma unroll
;             for (int bj = 0; bj < 2; ++bj)
; #pragma unroll
;                 for (int n = 0; n < 2; ++n) { f32x4 x = xc[bj][n] + (acc[ai][bj][m][n] + bv[bj][n]) * alpha; st16f_wt(X + off + bj * HALF + n * 16, x);
;                     if (XB) { u32x2w w; w.x = cvt_pk_bf16(x[0], x[1]); w.y = cvt_pk_bf16(x[2], x[3]); st8_wt(XB + off + bj * HALF + n * 16, w); }
;                     s += (x[0] * x[0] + x[1] * x[1]) + (x[2] * x[2] + x[3] * x[3]); }
.LBB0_643:
.LBB0_644:
	s_waitcnt lgkmcnt(0)
	v_lshlrev_b64 v[146:147], 10, v[220:221]
	v_lshl_add_u64 v[158:159], v[146:147], 0, v[218:219]
	v_pk_add_f32 v[146:147], v[48:49], v[144:145]
	v_pk_add_f32 v[160:161], v[46:47], v[142:143]
	s_waitcnt vmcnt(7)
	v_pk_fma_f32 v[148:149], v[146:147], s[94:95], v[188:189]
	v_pk_fma_f32 v[146:147], v[160:161], s[14:15], v[186:187]
	v_lshl_add_u64 v[172:173], v[158:159], 2, s[68:69]
	s_and_b64 vcc, exec, s[42:43]
	v_lshl_add_u64 v[170:171], v[158:159], 1, s[88:89]
	s_cbranch_vccz .LBB0_646
.LBB0_646:
	v_pk_add_f32 v[158:159], v[44:45], v[136:137]
	v_pk_add_f32 v[182:183], v[42:43], v[134:135]
	s_waitcnt vmcnt(6)
	v_pk_fma_f32 v[160:161], v[158:159], s[94:95], v[176:177]
	v_pk_fma_f32 v[158:159], v[182:183], s[14:15], v[174:175]
	v_bfe_i32 v175, v233, 3, 1
	v_and_b32_e32 v174, 0xffff8040, v175
	v_lshl_add_u64 v[172:173], v[172:173], 0, v[174:175]
	s_mov_b32 vcc_lo, 0x00ff00ff
	s_mov_b32 vcc_hi, 0x00ff00ff
	v_cndmask_b32_dpp v174, v158, v146, vcc row_ror:8 row_mask:0xf bank_mask:0xf
	v_cndmask_b32_dpp v175, v159, v147, vcc row_ror:8 row_mask:0xf bank_mask:0xf
	v_cndmask_b32_dpp v176, v160, v148, vcc row_ror:8 row_mask:0xf bank_mask:0xf
	v_cndmask_b32_dpp v177, v161, v149, vcc row_ror:8 row_mask:0xf bank_mask:0xf
	s_mov_b32 s2, 0x8000
	s_mov_b32 s3, 0
	global_store_dwordx4 v[172:173], v[174:177], off sc1
	s_not_b64 vcc, vcc
	v_lshl_add_u64 v[172:173], v[172:173], 0, s[2:3]
	s_nop 0
	v_cndmask_b32_dpp v174, v146, v158, vcc row_ror:8 row_mask:0xf bank_mask:0xf
	v_cndmask_b32_dpp v175, v147, v159, vcc row_ror:8 row_mask:0xf bank_mask:0xf
	v_cndmask_b32_dpp v176, v148, v160, vcc row_ror:8 row_mask:0xf bank_mask:0xf
	v_cndmask_b32_dpp v177, v149, v161, vcc row_ror:8 row_mask:0xf bank_mask:0xf
	s_nop 0
	global_store_dwordx4 v[172:173], v[174:177], off sc1
	s_nop 1
	s_and_b64 vcc, exec, s[42:43]
	s_cbranch_vccz .LBB0_648
	v_bfe_u32 v174, v233, 4, 1
	v_mul_u32_u24_e32 v174, 24, v174
	v_mov_b32_e32 v175, 0
	v_lshl_add_u64 v[170:171], v[170:171], 0, v[174:175]
	v_cvt_pk_bf16_f32 v174, v146, v147
	v_cvt_pk_bf16_f32 v175, v148, v149
	v_cvt_pk_bf16_f32 v176, v158, v159
	v_cvt_pk_bf16_f32 v177, v160, v161
	s_nop 1
	v_permlane16_swap_b32_e32 v174, v176
	v_permlane16_swap_b32_e32 v175, v177
	s_nop 1
	global_store_dwordx4 v[170:171], v[174:177], off sc1
	s_nop 1
.LBB0_648:
	v_pk_add_f32 v[174:175], v[16:17], v[140:141]
	v_pk_add_f32 v[176:177], v[14:15], v[138:139]
	s_mov_b64 s[2:3], 0x200
	s_waitcnt vmcnt(5)
	v_pk_fma_f32 v[164:165], v[174:175], s[94:95], v[164:165]
	v_pk_fma_f32 v[162:163], v[176:177], s[14:15], v[162:163]
	s_and_b64 vcc, exec, s[42:43]
	s_cbranch_vccz .LBB0_650
.LBB0_650:
	v_pk_add_f32 v[174:175], v[12:13], v[132:133]
	v_pk_add_f32 v[176:177], v[10:11], v[130:131]
	s_mov_b64 s[2:3], 0x240
	s_waitcnt vmcnt(4)
	v_pk_fma_f32 v[152:153], v[174:175], s[94:95], v[152:153]
	v_pk_fma_f32 v[150:151], v[176:177], s[14:15], v[150:151]
	s_mov_b32 vcc_lo, 0xff00ff00
	s_mov_b32 vcc_hi, 0xff00ff00
	v_cndmask_b32_dpp v174, v162, v150, vcc row_ror:8 row_mask:0xf bank_mask:0xf
	v_cndmask_b32_dpp v175, v163, v151, vcc row_ror:8 row_mask:0xf bank_mask:0xf
	v_cndmask_b32_dpp v176, v164, v152, vcc row_ror:8 row_mask:0xf bank_mask:0xf
	v_cndmask_b32_dpp v177, v165, v153, vcc row_ror:8 row_mask:0xf bank_mask:0xf
	s_mov_b32 s2, 0xffff8000
	s_mov_b32 s3, -1
	global_store_dwordx4 v[172:173], v[174:177], off offset:512 sc1
	s_not_b64 vcc, vcc
	v_lshl_add_u64 v[172:173], v[172:173], 0, s[2:3]
	s_nop 0
	v_cndmask_b32_dpp v174, v150, v162, vcc row_ror:8 row_mask:0xf bank_mask:0xf
	v_cndmask_b32_dpp v175, v151, v163, vcc row_ror:8 row_mask:0xf bank_mask:0xf
	v_cndmask_b32_dpp v176, v152, v164, vcc row_ror:8 row_mask:0xf bank_mask:0xf
	v_cndmask_b32_dpp v177, v153, v165, vcc row_ror:8 row_mask:0xf bank_mask:0xf
	s_nop 0
	global_store_dwordx4 v[172:173], v[174:177], off offset:512 sc1
	s_nop 1
	s_and_b64 vcc, exec, s[42:43]
	s_cbranch_vccz .LBB0_652
	v_cvt_pk_bf16_f32 v174, v162, v163
	v_cvt_pk_bf16_f32 v175, v164, v165
	v_cvt_pk_bf16_f32 v176, v150, v151
	v_cvt_pk_bf16_f32 v177, v152, v153
	s_nop 1
	v_permlane16_swap_b32_e32 v174, v176
	v_permlane16_swap_b32_e32 v175, v177
	s_nop 1
	global_store_dwordx4 v[170:171], v[174:177], off offset:256 sc1
	s_nop 1

; __device__ __forceinline__ unsigned cvt_pk_bf16(float lo, float hi) { unsigned r; asm volatile("v_cvt_pk_bf16_f32 %0, %1, %2" : "=v"(r) : "v"(lo), "v"(hi)); return r; }
; __device__ __forceinline__ void st16f_wt(void* p, f32x4 v) { asm volatile("global_store_dwordx4 %0, %1, off sc1\n\ts_nop 1" :: "v"(p), "v"(v) : "memory"); }
; __device__ __forceinline__ void st8_wt(void* p, u32x2w v) { asm volatile("global_store_dwordx2 %0, %1, off sc1\n\ts_nop 1" :: "v"(p), "v"(v) : "memory"); }
;     __device__ __forceinline__ void operator()(const f32x4 (&acc)[2][2][4][2], const Unit& u, int wr, int wc, int fr, int fq) const {
;     ...
;         for (int gi = 0; gi < 8; ++gi) { const int ai = gi >> 2, m = gi & 3; const int row = row0 + ai * HALF + m * 16; const size_t off = (size_t)row * 1024 + col0; float s = 0.f;
;             if (gi < 6) { const int ai2 = (gi + 2) >> 2, m2 = (gi + 2) & 3; const int rr = row0 + ai2 * HALF + m2 * 16; const float* rb = Xin0 ? (rr < NP ? Xin0 + (size_t)rr * 1024 : Xin1 + (size_t)(rr - NP) * 1024) : X + (size_t)rr * 1024;
; #pragma unroll
;                 for (int bj = 0; bj < 2; ++bj)
; #pragma unroll
;                     for (int n = 0; n < 2; ++n) xr[(gi + 2) % 3][bj][n] = ld16f_ag(rb + col0 + bj * HALF + n * 16); }
;             f32x4 xc[2][2];
; #pragma unroll
;             for (int bj = 0; bj < 2; ++bj)
; #pragma unroll
;                 for (int n = 0; n < 2; ++n) xc[bj][n] = xr[gi % 3][bj][n];
;             if (gi == 0) publish_prev(pendp, lane, xc[1][1][3]);
; #pragma unroll
;             for (int bj = 0; bj < 2; ++bj)
; #pragma unroll
;                 for (int n = 0; n < 2; ++n) { f32x4 x = xc[bj][n] + (acc[ai][bj][m][n] + bv[bj][n]) * alpha; st16f_wt(X + off + bj * HALF + n * 16, x);
;                     if (XB) { u32x2w w; w.x = cvt_pk_bf16(x[0], x[1]); w.y = cvt_pk_bf16(x[2], x[3]); st8_wt(XB + off + bj * HALF + n * 16, w); }
;                     s += (x[0] * x[0] + x[1] * x[1]) + (x[2] * x[2] + x[3] * x[3]); }
.LBB0_655:
.LBB0_656:
	s_waitcnt lgkmcnt(0)
	v_lshlrev_b64 v[146:147], 10, v[222:223]
	v_lshl_add_u64 v[146:147], v[146:147], 0, v[218:219]
	v_pk_add_f32 v[144:145], v[40:41], v[144:145]
	v_pk_add_f32 v[142:143], v[38:39], v[142:143]
	s_waitcnt vmcnt(3)
	v_pk_fma_f32 v[144:145], v[144:145], s[94:95], v[192:193]
	v_pk_fma_f32 v[142:143], v[142:143], s[14:15], v[190:191]
	v_lshl_add_u64 v[148:149], v[146:147], 2, s[68:69]
	s_and_b64 vcc, exec, s[42:43]
	v_lshl_add_u64 v[146:147], v[146:147], 1, s[88:89]
	s_cbranch_vccz .LBB0_658
.LBB0_658:
	v_pk_add_f32 v[136:137], v[36:37], v[136:137]
	v_pk_add_f32 v[134:135], v[34:35], v[134:135]
	s_waitcnt vmcnt(2)
	v_pk_fma_f32 v[136:137], v[136:137], s[94:95], v[180:181]
	v_pk_fma_f32 v[134:135], v[134:135], s[14:15], v[178:179]
	v_bfe_i32 v151, v233, 3, 1
	v_and_b32_e32 v150, 0xffff8040, v151
	v_lshl_add_u64 v[148:149], v[148:149], 0, v[150:151]
	s_mov_b32 vcc_lo, 0x00ff00ff
	s_mov_b32 vcc_hi, 0x00ff00ff
	v_cndmask_b32_dpp v150, v134, v142, vcc row_ror:8 row_mask:0xf bank_mask:0xf
	v_cndmask_b32_dpp v151, v135, v143, vcc row_ror:8 row_mask:0xf bank_mask:0xf
	v_cndmask_b32_dpp v152, v136, v144, vcc row_ror:8 row_mask:0xf bank_mask:0xf
	v_cndmask_b32_dpp v153, v137, v145, vcc row_ror:8 row_mask:0xf bank_mask:0xf
	s_mov_b32 s2, 0x8000
	s_mov_b32 s3, 0
	global_store_dwordx4 v[148:149], v[150:153], off sc1
	s_not_b64 vcc, vcc
	v_lshl_add_u64 v[148:149], v[148:149], 0, s[2:3]
	s_nop 0
	v_cndmask_b32_dpp v150, v142, v134, vcc row_ror:8 row_mask:0xf bank_mask:0xf
	v_cndmask_b32_dpp v151, v143, v135, vcc row_ror:8 row_mask:0xf bank_mask:0xf
	v_cndmask_b32_dpp v152, v144, v136, vcc row_ror:8 row_mask:0xf bank_mask:0xf
	v_cndmask_b32_dpp v153, v145, v137, vcc row_ror:8 row_mask:0xf bank_mask:0xf
	s_nop 0
	global_store_dwordx4 v[148:149], v[150:153], off sc1
	s_nop 1
	s_and_b64 vcc, exec, s[42:43]
	s_cbranch_vccz .LBB0_660
	v_bfe_u32 v150, v233, 4, 1
	v_mul_u32_u24_e32 v150, 24, v150
	v_mov_b32_e32 v151, 0
	v_lshl_add_u64 v[146:147], v[146:147], 0, v[150:151]
	v_cvt_pk_bf16_f32 v150, v142, v143
	v_cvt_pk_bf16_f32 v151, v144, v145
	v_cvt_pk_bf16_f32 v152, v134, v135
	v_cvt_pk_bf16_f32 v153, v136, v137
	s_nop 1
	v_permlane16_swap_b32_e32 v150, v152
	v_permlane16_swap_b32_e32 v151, v153
	s_nop 1
	global_store_dwordx4 v[146:147], v[150:153], off sc1
	s_nop 1
.LBB0_660:
	v_pk_add_f32 v[140:141], v[8:9], v[140:141]
	v_pk_add_f32 v[138:139], v[6:7], v[138:139]
	s_mov_b64 s[2:3], 0x200
	s_waitcnt vmcnt(1)
	v_pk_fma_f32 v[140:141], v[140:141], s[94:95], v[168:169]
	v_pk_fma_f32 v[138:139], v[138:139], s[14:15], v[166:167]
	s_and_b64 vcc, exec, s[42:43]
	s_cbranch_vccz .LBB0_662
.LBB0_662:
	v_pk_add_f32 v[132:133], v[4:5], v[132:133]
	v_pk_add_f32 v[130:131], v[2:3], v[130:131]
	s_mov_b64 s[2:3], 0x240
	s_waitcnt vmcnt(0)
	v_pk_fma_f32 v[132:133], v[132:133], s[94:95], v[156:157]
	v_pk_fma_f32 v[130:131], v[130:131], s[14:15], v[154:155]
	s_mov_b32 vcc_lo, 0xff00ff00
	s_mov_b32 vcc_hi, 0xff00ff00
	v_cndmask_b32_dpp v150, v138, v130, vcc row_ror:8 row_mask:0xf bank_mask:0xf
	v_cndmask_b32_dpp v151, v139, v131, vcc row_ror:8 row_mask:0xf bank_mask:0xf
	v_cndmask_b32_dpp v152, v140, v132, vcc row_ror:8 row_mask:0xf bank_mask:0xf
	v_cndmask_b32_dpp v153, v141, v133, vcc row_ror:8 row_mask:0xf bank_mask:0xf
	s_mov_b32 s2, 0xffff8000
	s_mov_b32 s3, -1
	global_store_dwordx4 v[148:149], v[150:153], off offset:512 sc1
	s_not_b64 vcc, vcc
	v_lshl_add_u64 v[148:149], v[148:149], 0, s[2:3]
	s_nop 0
	v_cndmask_b32_dpp v150, v130, v138, vcc row_ror:8 row_mask:0xf bank_mask:0xf
	v_cndmask_b32_dpp v151, v131, v139, vcc row_ror:8 row_mask:0xf bank_mask:0xf
	v_cndmask_b32_dpp v152, v132, v140, vcc row_ror:8 row_mask:0xf bank_mask:0xf
	v_cndmask_b32_dpp v153, v133, v141, vcc row_ror:8 row_mask:0xf bank_mask:0xf
	s_nop 0
	global_store_dwordx4 v[148:149], v[150:153], off offset:512 sc1
	s_nop 1
	s_and_b64 vcc, exec, s[42:43]
	s_cbranch_vccz .LBB0_664
	v_cvt_pk_bf16_f32 v150, v138, v139
	v_cvt_pk_bf16_f32 v151, v140, v141
	v_cvt_pk_bf16_f32 v152, v130, v131
	v_cvt_pk_bf16_f32 v153, v132, v133
	s_nop 1
	v_permlane16_swap_b32_e32 v150, v152
	v_permlane16_swap_b32_e32 v151, v153
	s_nop 1
	global_store_dwordx4 v[146:147], v[150:153], off offset:256 sc1
	s_nop 1
